# v61 + MLP1 relu^2 epilogue re-emitted from traced dataflow: squares via v_pk_mul_f32 (264 instead of 336 VALU per tile), same values and stores
# speedup vs baseline: 1.0036x; 1.0036x over previous
; __device__ __forceinline__ unsigned cvt_pk_bf16(float lo, float hi) { unsigned r; asm volatile("v_cvt_pk_bf16_f32 %0, %1, %2" : "=v"(r) : "v"(lo), "v"(hi)); return r; }
; #define PG8_OPQ(p) asm volatile("" : "+v"(p))
;     __device__ __forceinline__ void operator()(const f32x4 (&acc)[2][2][4][2], const Unit& u, int wr, int wc, int fr, int fq) const {
;     ...
;             for (int m = 0; m < 4; ++m) {
;                 PG8_OPQ(p);
; #pragma unroll
;                 for (int bj = 0; bj < 2; ++bj) { f32x4 v0 = acc[ai][bj][m][0], v1 = acc[ai][bj][m][1];
;                     if (ACT == 1) {
; #pragma unroll
;                         for (int j = 0; j < 4; ++j) { const float a0 = fmaxf(v0[j], 0.f), a1 = fmaxf(v1[j], 0.f); v0[j] = a0 * a0; v1[j] = a1 * a1; } }
;                     u32x4 w; w.x = cvt_pk_bf16(v0[0], v0[1]); w.y = cvt_pk_bf16(v0[2], v0[3]); w.z = cvt_pk_bf16(v1[0], v1[1]); w.w = cvt_pk_bf16(v1[2], v1[3]);
;                     *(u32x4*)(p + bj * HALF * 2) = w; }
;                 p += step;
.LBB0_438:
	s_lshr_b32 s36, s8, 2
	s_lshl_b32 s36, s36, 23
	s_and_b32 s99, s8, 3
	s_lshl_b32 s99, s99, 8
	s_add_u32 s36, s36, s99
	s_lshr_b32 s99, s98, 14
	s_add_u32 s36, s36, s99
	v_lshl_add_u64 v[144:145], s[36:37], 1, v[136:137]
	v_max3_f32 v122, v122, v122, 0
	v_max3_f32 v123, v123, v123, 0
	v_max3_f32 v124, v124, v124, 0
	v_max3_f32 v125, v125, v125, 0
	v_max3_f32 v126, v126, v126, 0
	v_max3_f32 v127, v127, v127, 0
	v_max3_f32 v128, v128, v128, 0
	v_max3_f32 v129, v129, v129, 0
	v_pk_mul_f32 v[122:123], v[122:123], v[122:123]
	v_pk_mul_f32 v[124:125], v[124:125], v[124:125]
	v_pk_mul_f32 v[126:127], v[126:127], v[126:127]
	v_pk_mul_f32 v[128:129], v[128:129], v[128:129]
	v_cvt_pk_bf16_f32 v122, v122, v123
	v_cvt_pk_bf16_f32 v123, v124, v125
	v_cvt_pk_bf16_f32 v124, v126, v127
	v_cvt_pk_bf16_f32 v125, v128, v129
	global_store_dwordx4 v[144:145], v[122:125], off
	s_nop 1
	v_max3_f32 v118, v118, v118, 0
	v_max3_f32 v119, v119, v119, 0
	v_max3_f32 v120, v120, v120, 0
	v_max3_f32 v121, v121, v121, 0
	v_max3_f32 v114, v114, v114, 0
	v_max3_f32 v115, v115, v115, 0
	v_max3_f32 v116, v116, v116, 0
	v_max3_f32 v117, v117, v117, 0
	v_pk_mul_f32 v[118:119], v[118:119], v[118:119]
	v_pk_mul_f32 v[120:121], v[120:121], v[120:121]
	v_pk_mul_f32 v[114:115], v[114:115], v[114:115]
	v_pk_mul_f32 v[116:117], v[116:117], v[116:117]
	v_cvt_pk_bf16_f32 v118, v118, v119
	v_cvt_pk_bf16_f32 v119, v120, v121
	v_cvt_pk_bf16_f32 v120, v114, v115
	v_cvt_pk_bf16_f32 v121, v116, v117
	global_store_dwordx4 v[144:145], v[118:121], off offset:256
	s_nop 1
	v_lshl_add_u64 v[114:115], v[144:145], 0, s[16:17]
	v_max3_f32 v110, v110, v110, 0
	v_max3_f32 v111, v111, v111, 0
	v_max3_f32 v112, v112, v112, 0
	v_max3_f32 v113, v113, v113, 0
	v_max3_f32 v106, v106, v106, 0
	v_max3_f32 v107, v107, v107, 0
	v_max3_f32 v108, v108, v108, 0
	v_max3_f32 v109, v109, v109, 0
	v_pk_mul_f32 v[110:111], v[110:111], v[110:111]
	v_pk_mul_f32 v[112:113], v[112:113], v[112:113]
	v_pk_mul_f32 v[106:107], v[106:107], v[106:107]
	v_pk_mul_f32 v[108:109], v[108:109], v[108:109]
	v_cvt_pk_bf16_f32 v110, v110, v111
	v_cvt_pk_bf16_f32 v111, v112, v113
	v_cvt_pk_bf16_f32 v112, v106, v107
	v_cvt_pk_bf16_f32 v113, v108, v109
	global_store_dwordx4 v[114:115], v[110:113], off
	s_nop 1
	v_max3_f32 v102, v102, v102, 0
	v_max3_f32 v103, v103, v103, 0
	v_max3_f32 v104, v104, v104, 0
	v_max3_f32 v105, v105, v105, 0
	v_max3_f32 v98, v98, v98, 0
	v_max3_f32 v99, v99, v99, 0
	v_max3_f32 v100, v100, v100, 0
	v_max3_f32 v101, v101, v101, 0
	v_pk_mul_f32 v[102:103], v[102:103], v[102:103]
	v_pk_mul_f32 v[104:105], v[104:105], v[104:105]
	v_pk_mul_f32 v[98:99], v[98:99], v[98:99]
	v_pk_mul_f32 v[100:101], v[100:101], v[100:101]
	v_cvt_pk_bf16_f32 v102, v102, v103
	v_cvt_pk_bf16_f32 v103, v104, v105
	v_cvt_pk_bf16_f32 v104, v98, v99
	v_cvt_pk_bf16_f32 v105, v100, v101
	global_store_dwordx4 v[114:115], v[102:105], off offset:256
	s_nop 1
	v_lshl_add_u64 v[98:99], v[114:115], 0, s[16:17]
	v_max3_f32 v94, v94, v94, 0
	v_max3_f32 v95, v95, v95, 0
	v_max3_f32 v96, v96, v96, 0
	v_max3_f32 v97, v97, v97, 0
	v_max3_f32 v90, v90, v90, 0
	v_max3_f32 v91, v91, v91, 0
	v_max3_f32 v92, v92, v92, 0
	v_max3_f32 v93, v93, v93, 0
	v_pk_mul_f32 v[94:95], v[94:95], v[94:95]
	v_pk_mul_f32 v[96:97], v[96:97], v[96:97]
	v_pk_mul_f32 v[90:91], v[90:91], v[90:91]
	v_pk_mul_f32 v[92:93], v[92:93], v[92:93]
	v_cvt_pk_bf16_f32 v94, v94, v95
	v_cvt_pk_bf16_f32 v95, v96, v97
	v_cvt_pk_bf16_f32 v96, v90, v91
	v_cvt_pk_bf16_f32 v97, v92, v93
	global_store_dwordx4 v[98:99], v[94:97], off
	s_nop 1
	v_max3_f32 v86, v86, v86, 0
	v_max3_f32 v87, v87, v87, 0
	v_max3_f32 v88, v88, v88, 0
	v_max3_f32 v89, v89, v89, 0
	v_max3_f32 v82, v82, v82, 0
	v_max3_f32 v83, v83, v83, 0
	v_max3_f32 v84, v84, v84, 0
	v_max3_f32 v85, v85, v85, 0
	v_pk_mul_f32 v[86:87], v[86:87], v[86:87]
	v_pk_mul_f32 v[88:89], v[88:89], v[88:89]
	v_pk_mul_f32 v[82:83], v[82:83], v[82:83]
	v_pk_mul_f32 v[84:85], v[84:85], v[84:85]
	v_cvt_pk_bf16_f32 v86, v86, v87
	v_cvt_pk_bf16_f32 v87, v88, v89
	v_cvt_pk_bf16_f32 v88, v82, v83
	v_cvt_pk_bf16_f32 v89, v84, v85
	global_store_dwordx4 v[98:99], v[86:89], off offset:256
	s_nop 1
	v_lshl_add_u64 v[82:83], v[98:99], 0, s[16:17]
	v_max3_f32 v78, v78, v78, 0
	v_max3_f32 v79, v79, v79, 0
	v_max3_f32 v80, v80, v80, 0
	v_max3_f32 v81, v81, v81, 0
	v_max3_f32 v74, v74, v74, 0
	v_max3_f32 v75, v75, v75, 0
	v_max3_f32 v76, v76, v76, 0
	v_max3_f32 v77, v77, v77, 0
	v_pk_mul_f32 v[78:79], v[78:79], v[78:79]
	v_pk_mul_f32 v[80:81], v[80:81], v[80:81]
	v_pk_mul_f32 v[74:75], v[74:75], v[74:75]
	v_pk_mul_f32 v[76:77], v[76:77], v[76:77]
	v_cvt_pk_bf16_f32 v78, v78, v79
	v_cvt_pk_bf16_f32 v79, v80, v81
	v_cvt_pk_bf16_f32 v80, v74, v75
	v_cvt_pk_bf16_f32 v81, v76, v77
	global_store_dwordx4 v[82:83], v[78:81], off
	s_nop 1
	v_max3_f32 v70, v70, v70, 0
	v_max3_f32 v71, v71, v71, 0
	v_max3_f32 v72, v72, v72, 0
	v_max3_f32 v73, v73, v73, 0
	v_max3_f32 v66, v66, v66, 0
	v_max3_f32 v67, v67, v67, 0
	v_max3_f32 v68, v68, v68, 0
	v_max3_f32 v69, v69, v69, 0
	v_pk_mul_f32 v[70:71], v[70:71], v[70:71]
	v_pk_mul_f32 v[72:73], v[72:73], v[72:73]
	v_pk_mul_f32 v[66:67], v[66:67], v[66:67]
	v_pk_mul_f32 v[68:69], v[68:69], v[68:69]
	v_cvt_pk_bf16_f32 v70, v70, v71
; __device__ __forceinline__ unsigned cvt_pk_bf16(float lo, float hi) { unsigned r; asm volatile("v_cvt_pk_bf16_f32 %0, %1, %2" : "=v"(r) : "v"(lo), "v"(hi)); return r; }
; #define PG8_OPQ(p) asm volatile("" : "+v"(p))
;     __device__ __forceinline__ void operator()(const f32x4 (&acc)[2][2][4][2], const Unit& u, int wr, int wc, int fr, int fq) const {
;     ...
;             for (int m = 0; m < 4; ++m) {
;                 PG8_OPQ(p);
; #pragma unroll
;                 for (int bj = 0; bj < 2; ++bj) { f32x4 v0 = acc[ai][bj][m][0], v1 = acc[ai][bj][m][1];
;                     if (ACT == 1) {
; #pragma unroll
;                         for (int j = 0; j < 4; ++j) { const float a0 = fmaxf(v0[j], 0.f), a1 = fmaxf(v1[j], 0.f); v0[j] = a0 * a0; v1[j] = a1 * a1; } }
;                     u32x4 w; w.x = cvt_pk_bf16(v0[0], v0[1]); w.y = cvt_pk_bf16(v0[2], v0[3]); w.z = cvt_pk_bf16(v1[0], v1[1]); w.w = cvt_pk_bf16(v1[2], v1[3]);
;                     *(u32x4*)(p + bj * HALF * 2) = w; }
;                 p += step;
	v_cvt_pk_bf16_f32 v71, v72, v73
	v_cvt_pk_bf16_f32 v72, v66, v67
	v_cvt_pk_bf16_f32 v73, v68, v69
	global_store_dwordx4 v[82:83], v[70:73], off offset:256
	s_nop 1
	s_mov_b64 s[48:49], 0xa0000
	v_lshl_add_u64 v[66:67], v[82:83], 0, s[48:49]
	v_max3_f32 v62, v62, v62, 0
	v_max3_f32 v63, v63, v63, 0
	v_max3_f32 v64, v64, v64, 0
	v_max3_f32 v65, v65, v65, 0
	v_max3_f32 v58, v58, v58, 0
	v_max3_f32 v59, v59, v59, 0
	v_max3_f32 v60, v60, v60, 0
	v_max3_f32 v61, v61, v61, 0
	v_pk_mul_f32 v[62:63], v[62:63], v[62:63]
	v_pk_mul_f32 v[64:65], v[64:65], v[64:65]
	v_pk_mul_f32 v[58:59], v[58:59], v[58:59]
	v_pk_mul_f32 v[60:61], v[60:61], v[60:61]
	v_cvt_pk_bf16_f32 v62, v62, v63
	v_cvt_pk_bf16_f32 v63, v64, v65
	v_cvt_pk_bf16_f32 v64, v58, v59
	v_cvt_pk_bf16_f32 v65, v60, v61
	global_store_dwordx4 v[66:67], v[62:65], off
	s_nop 1
	v_max3_f32 v54, v54, v54, 0
	v_max3_f32 v55, v55, v55, 0
	v_max3_f32 v56, v56, v56, 0
	v_max3_f32 v57, v57, v57, 0
	v_max3_f32 v50, v50, v50, 0
	v_max3_f32 v51, v51, v51, 0
	v_max3_f32 v52, v52, v52, 0
	v_max3_f32 v53, v53, v53, 0
	v_pk_mul_f32 v[54:55], v[54:55], v[54:55]
	v_pk_mul_f32 v[56:57], v[56:57], v[56:57]
	v_pk_mul_f32 v[50:51], v[50:51], v[50:51]
	v_pk_mul_f32 v[52:53], v[52:53], v[52:53]
	v_cvt_pk_bf16_f32 v54, v54, v55
	v_cvt_pk_bf16_f32 v55, v56, v57
	v_cvt_pk_bf16_f32 v56, v50, v51
	v_cvt_pk_bf16_f32 v57, v52, v53
	global_store_dwordx4 v[66:67], v[54:57], off offset:256
	s_nop 1
	v_lshl_add_u64 v[50:51], v[66:67], 0, s[16:17]
	v_max3_f32 v46, v46, v46, 0
	v_max3_f32 v47, v47, v47, 0
	v_max3_f32 v48, v48, v48, 0
	v_max3_f32 v49, v49, v49, 0
	v_max3_f32 v42, v42, v42, 0
	v_max3_f32 v43, v43, v43, 0
	v_max3_f32 v44, v44, v44, 0
	v_max3_f32 v45, v45, v45, 0
	v_pk_mul_f32 v[46:47], v[46:47], v[46:47]
	v_pk_mul_f32 v[48:49], v[48:49], v[48:49]
	v_pk_mul_f32 v[42:43], v[42:43], v[42:43]
	v_pk_mul_f32 v[44:45], v[44:45], v[44:45]
	v_cvt_pk_bf16_f32 v46, v46, v47
	v_cvt_pk_bf16_f32 v47, v48, v49
	v_cvt_pk_bf16_f32 v48, v42, v43
	v_cvt_pk_bf16_f32 v49, v44, v45
	global_store_dwordx4 v[50:51], v[46:49], off
	s_nop 1
	v_max3_f32 v38, v38, v38, 0
	v_max3_f32 v39, v39, v39, 0
	v_max3_f32 v40, v40, v40, 0
	v_max3_f32 v41, v41, v41, 0
	v_max3_f32 v34, v34, v34, 0
	v_max3_f32 v35, v35, v35, 0
	v_max3_f32 v36, v36, v36, 0
	v_max3_f32 v37, v37, v37, 0
	v_pk_mul_f32 v[38:39], v[38:39], v[38:39]
	v_pk_mul_f32 v[40:41], v[40:41], v[40:41]
	v_pk_mul_f32 v[34:35], v[34:35], v[34:35]
	v_pk_mul_f32 v[36:37], v[36:37], v[36:37]
	v_cvt_pk_bf16_f32 v38, v38, v39
	v_cvt_pk_bf16_f32 v39, v40, v41
	v_cvt_pk_bf16_f32 v40, v34, v35
	v_cvt_pk_bf16_f32 v41, v36, v37
	global_store_dwordx4 v[50:51], v[38:41], off offset:256
	s_nop 1
	v_lshl_add_u64 v[34:35], v[50:51], 0, s[16:17]
	v_max3_f32 v30, v30, v30, 0
	v_max3_f32 v31, v31, v31, 0
	v_max3_f32 v32, v32, v32, 0
	v_max3_f32 v33, v33, v33, 0
	v_max3_f32 v26, v26, v26, 0
	v_max3_f32 v27, v27, v27, 0
	v_max3_f32 v28, v28, v28, 0
	v_max3_f32 v29, v29, v29, 0
	v_pk_mul_f32 v[30:31], v[30:31], v[30:31]
	v_pk_mul_f32 v[32:33], v[32:33], v[32:33]
	v_pk_mul_f32 v[26:27], v[26:27], v[26:27]
	v_pk_mul_f32 v[28:29], v[28:29], v[28:29]
	v_cvt_pk_bf16_f32 v30, v30, v31
	v_cvt_pk_bf16_f32 v31, v32, v33
	v_cvt_pk_bf16_f32 v32, v26, v27
	v_cvt_pk_bf16_f32 v33, v28, v29
	global_store_dwordx4 v[34:35], v[30:33], off
	s_nop 1
	v_max3_f32 v22, v22, v22, 0
	v_max3_f32 v23, v23, v23, 0
	v_max3_f32 v24, v24, v24, 0
	v_max3_f32 v25, v25, v25, 0
	v_max3_f32 v18, v18, v18, 0
	v_max3_f32 v19, v19, v19, 0
	v_max3_f32 v20, v20, v20, 0
	v_max3_f32 v21, v21, v21, 0
	v_pk_mul_f32 v[22:23], v[22:23], v[22:23]
	v_pk_mul_f32 v[24:25], v[24:25], v[24:25]
	v_pk_mul_f32 v[18:19], v[18:19], v[18:19]
	v_pk_mul_f32 v[20:21], v[20:21], v[20:21]
	v_cvt_pk_bf16_f32 v22, v22, v23
	v_cvt_pk_bf16_f32 v23, v24, v25
	v_cvt_pk_bf16_f32 v24, v18, v19
	v_cvt_pk_bf16_f32 v25, v20, v21
	global_store_dwordx4 v[34:35], v[22:25], off offset:256
	s_nop 1
	v_lshl_add_u64 v[18:19], v[34:35], 0, s[16:17]
	v_max3_f32 v14, v14, v14, 0
	v_max3_f32 v15, v15, v15, 0
	v_max3_f32 v16, v16, v16, 0
	v_max3_f32 v17, v17, v17, 0
	v_max3_f32 v10, v10, v10, 0
	v_max3_f32 v11, v11, v11, 0
	v_max3_f32 v12, v12, v12, 0
	v_max3_f32 v13, v13, v13, 0
	v_pk_mul_f32 v[14:15], v[14:15], v[14:15]
	v_pk_mul_f32 v[16:17], v[16:17], v[16:17]
	v_pk_mul_f32 v[10:11], v[10:11], v[10:11]
	v_pk_mul_f32 v[12:13], v[12:13], v[12:13]
	v_cvt_pk_bf16_f32 v14, v14, v15
	v_cvt_pk_bf16_f32 v15, v16, v17
	v_cvt_pk_bf16_f32 v16, v10, v11
	v_cvt_pk_bf16_f32 v17, v12, v13
	global_store_dwordx4 v[18:19], v[14:17], off
	s_nop 1
	v_max3_f32 v6, v6, v6, 0
	v_max3_f32 v7, v7, v7, 0
	v_max3_f32 v8, v8, v8, 0
	v_max3_f32 v9, v9, v9, 0
	v_max3_f32 v2, v2, v2, 0
	v_max3_f32 v3, v3, v3, 0
	v_max3_f32 v4, v4, v4, 0
	v_max3_f32 v5, v5, v5, 0
	v_pk_mul_f32 v[6:7], v[6:7], v[6:7]
	v_pk_mul_f32 v[8:9], v[8:9], v[8:9]
	v_pk_mul_f32 v[2:3], v[2:3], v[2:3]
	v_pk_mul_f32 v[4:5], v[4:5], v[4:5]
	v_cvt_pk_bf16_f32 v6, v6, v7
	v_cvt_pk_bf16_f32 v7, v8, v9
	v_cvt_pk_bf16_f32 v8, v2, v3
	v_cvt_pk_bf16_f32 v9, v4, v5
	global_store_dwordx4 v[18:19], v[6:9], off offset:256
	s_nop 1
	s_cmp_eq_u32 s8, 15
	s_mov_b64 s[8:9], -1
	s_cbranch_scc1 .LBB0_430
	s_andn2_b64 vcc, exec, s[38:39]
	s_cbranch_vccnz .LBB0_429
	s_barrier
	s_branch .LBB0_429
